# GEMM epilogue row-scale table rebuilt in LDS once when the tile's row panel changes (was 8 serialized memory round trips per such tile)
# baseline (speedup 1.0000x reference)
.LBB0_154:
	s_cmp_lt_i32 s4, 0
	s_cbranch_scc1 .Lrs_e1
	s_bitcmp0_b32 s4, 8
	s_cbranch_scc1 .Lrs_e1
	s_bitset0_b32 s4, 8
	s_barrier

.Lzp_exit1:
	s_cmp_eq_u32 s20, s4
	s_cbranch_scc1 .Lrs_ok1
	s_mov_b32 s4, s20
	v_cmp_gt_i32_e32 vcc, 0x100, v156
	s_cbranch_vccnz .Lrs_a1
	s_bitset1_b32 s4, 8
	s_branch .Lrs_ok1
.Lrs_a1:
	v_lshl_add_u32 v146, s20, 8, v156
	v_ashrrev_i32_e32 v147, 31, v146
	v_lshlrev_b64 v[146:147], 6, v[146:147]
	v_lshl_add_u64 v[154:155], s[94:95], 0, v[146:147]
	global_load_dwordx4 v[128:131], v[154:155], off
	global_load_dwordx4 v[132:135], v[154:155], off offset:16
	global_load_dwordx4 v[136:139], v[154:155], off offset:32
	global_load_dwordx4 v[146:149], v[154:155], off offset:48
	v_lshl_add_u32 v150, v156, 2, 0
	v_add_u32_e32 v150, 0x20000, v150
	s_waitcnt vmcnt(0)
	v_mov_b32_e32 v152, v129
	v_mov_b32_e32 v153, v130
	v_mov_b32_e32 v129, v131
	v_mov_b32_e32 v130, v133
	v_mov_b32_e32 v131, v134
	v_mov_b32_e32 v133, v135
	v_pk_add_f32 v[128:129], v[152:153], v[128:129]
	v_pk_add_f32 v[130:131], v[130:131], v[132:133]
	v_pk_add_f32 v[128:129], v[128:129], v[128:129] op_sel:[0,1] op_sel_hi:[1,0]
	v_pk_add_f32 v[130:131], v[130:131], v[130:131] op_sel:[0,1] op_sel_hi:[1,0]
	v_add_f32_e32 v134, v136, v137
	v_add_f32_e32 v136, v138, v139
	v_mov_b32_e32 v135, v148
	v_mov_b32_e32 v137, v149
	v_mov_b32_e32 v129, v146
	v_mov_b32_e32 v131, v147
	v_pk_add_f32 v[132:133], v[134:135], v[136:137]
	v_pk_add_f32 v[128:129], v[128:129], v[130:131]
	s_nop 0
	v_pk_add_f32 v[128:129], v[128:129], v[132:133]
	s_nop 0
	v_add_f32_e32 v151, v128, v129
	v_fmamk_f32 v151, v151, 0x3a800000, v193
	v_mul_f32_e32 v152, 0x4b800000, v151
	v_cmp_gt_f32_e32 vcc, s40, v151
	s_nop 1
	v_cndmask_b32_e32 v151, v151, v152, vcc
	v_rsq_f32_e32 v151, v151
	s_nop 0
	v_mul_f32_e32 v152, 0x45800000, v151
	v_cndmask_b32_e32 v151, v151, v152, vcc
	ds_write_b32 v150, v151
	s_waitcnt lgkmcnt(0)
	s_barrier
.Lrs_ok1:
	s_lshl_b32 s11, s20, 8
	s_cmp_lg_u32 s20, s20
	s_cselect_b64 s[20:21], -1, 0
	v_add_u32_e32 v138, s11, v141
	s_mov_b64 s[22:23], -1
	s_and_b64 vcc, exec, s[20:21]
	s_cbranch_vccz .LBB0_165
	v_ashrrev_i32_e32 v139, 31, v138
	v_lshlrev_b64 v[146:147], 6, v[138:139]
	v_lshl_add_u64 v[154:155], s[94:95], 0, v[146:147]
	global_load_dwordx4 v[146:149], v[154:155], off offset:48
	global_load_dwordx4 v[150:153], v[154:155], off offset:32
	global_load_dwordx4 v[166:169], v[154:155], off offset:16
	global_load_dwordx4 v[170:173], v[154:155], off
	s_mov_b64 s[22:23], 0
	s_waitcnt vmcnt(0)
	v_add_f32_e32 v150, v150, v151
	v_add_f32_e32 v152, v152, v153
	v_mov_b32_e32 v154, v171
	v_mov_b32_e32 v155, v172
	v_mov_b32_e32 v171, v173
	v_pk_add_f32 v[154:155], v[154:155], v[170:171]
	v_mov_b32_e32 v170, v167
	v_mov_b32_e32 v171, v168
	v_mov_b32_e32 v167, v169
	v_pk_add_f32 v[166:167], v[170:171], v[166:167]
	v_pk_add_f32 v[154:155], v[154:155], v[154:155] op_sel:[0,1] op_sel_hi:[1,0]
	v_pk_add_f32 v[166:167], v[166:167], v[166:167] op_sel:[0,1] op_sel_hi:[1,0]
	v_mov_b32_e32 v155, v146
	v_mov_b32_e32 v167, v147
	v_mov_b32_e32 v151, v148
	v_mov_b32_e32 v153, v149
	v_pk_add_f32 v[146:147], v[154:155], v[166:167]
	v_pk_add_f32 v[148:149], v[150:151], v[152:153]
	s_nop 0
	v_pk_add_f32 v[146:147], v[146:147], v[148:149]
	s_nop 0
	v_add_f32_e32 v139, v146, v147
	v_fmamk_f32 v139, v139, 0x3a800000, v193
	v_cmp_gt_f32_e32 vcc, s40, v139
	v_mul_f32_e32 v140, 0x4b800000, v139
	s_nop 0
	v_cndmask_b32_e32 v139, v139, v140, vcc
	v_rsq_f32_e32 v139, v139
	s_nop 0
	v_mul_f32_e32 v140, 0x45800000, v139
	v_cndmask_b32_e32 v140, v139, v140, vcc

.Lzp_exit2:
	s_cmp_eq_u32 s22, s4
	s_cbranch_scc1 .Lrs_ok2
	s_mov_b32 s4, s22
	v_cmp_gt_i32_e32 vcc, 0x100, v156
	s_cbranch_vccnz .Lrs_a2
	s_bitset1_b32 s4, 8
	s_branch .Lrs_ok2
.Lrs_a2:
	v_lshl_add_u32 v146, s22, 8, v156
	v_ashrrev_i32_e32 v147, 31, v146
	v_lshlrev_b64 v[146:147], 6, v[146:147]
	v_lshl_add_u64 v[154:155], s[94:95], 0, v[146:147]
	global_load_dwordx4 v[128:131], v[154:155], off
	global_load_dwordx4 v[132:135], v[154:155], off offset:16
	global_load_dwordx4 v[136:139], v[154:155], off offset:32
	global_load_dwordx4 v[146:149], v[154:155], off offset:48
	v_lshl_add_u32 v150, v156, 2, 0
	v_add_u32_e32 v150, 0x20000, v150
	s_waitcnt vmcnt(0)
	v_mov_b32_e32 v152, v129
	v_mov_b32_e32 v153, v130
	v_mov_b32_e32 v129, v131
	v_mov_b32_e32 v130, v133
	v_mov_b32_e32 v131, v134
	v_mov_b32_e32 v133, v135
	v_pk_add_f32 v[128:129], v[152:153], v[128:129]
	v_pk_add_f32 v[130:131], v[130:131], v[132:133]
	v_pk_add_f32 v[128:129], v[128:129], v[128:129] op_sel:[0,1] op_sel_hi:[1,0]
	v_pk_add_f32 v[130:131], v[130:131], v[130:131] op_sel:[0,1] op_sel_hi:[1,0]
	v_add_f32_e32 v134, v136, v137
	v_add_f32_e32 v136, v138, v139
	v_mov_b32_e32 v135, v148
	v_mov_b32_e32 v137, v149
	v_mov_b32_e32 v129, v146
	v_mov_b32_e32 v131, v147
	v_pk_add_f32 v[132:133], v[134:135], v[136:137]
	v_pk_add_f32 v[128:129], v[128:129], v[130:131]
	s_nop 0
	v_pk_add_f32 v[128:129], v[128:129], v[132:133]
	s_nop 0
	v_add_f32_e32 v151, v128, v129
	v_fmamk_f32 v151, v151, 0x3a800000, v193
	v_mul_f32_e32 v152, 0x4b800000, v151
	v_cmp_gt_f32_e32 vcc, s40, v151
	s_nop 1
	v_cndmask_b32_e32 v151, v151, v152, vcc
	v_rsq_f32_e32 v151, v151
	s_nop 0
	v_mul_f32_e32 v152, 0x45800000, v151
	v_cndmask_b32_e32 v151, v151, v152, vcc
	ds_write_b32 v150, v151
	s_waitcnt lgkmcnt(0)
	s_barrier
.Lrs_ok2:
	s_lshl_b32 s11, s22, 8
	s_cmp_lg_u32 s22, s22
	s_cselect_b64 s[22:23], -1, 0
	v_add_u32_e32 v138, s11, v141
	s_mov_b64 s[24:25], -1
	s_and_b64 vcc, exec, s[22:23]
	s_cbranch_vccz .LBB0_537
	v_ashrrev_i32_e32 v139, 31, v138
	v_lshlrev_b64 v[146:147], 6, v[138:139]
	v_lshl_add_u64 v[154:155], s[94:95], 0, v[146:147]
	global_load_dwordx4 v[146:149], v[154:155], off offset:48
	global_load_dwordx4 v[150:153], v[154:155], off offset:32
	global_load_dwordx4 v[166:169], v[154:155], off offset:16
	global_load_dwordx4 v[170:173], v[154:155], off
	s_mov_b64 s[24:25], 0
	s_waitcnt vmcnt(0)
	v_add_f32_e32 v150, v150, v151
	v_add_f32_e32 v152, v152, v153
	v_mov_b32_e32 v154, v171
	v_mov_b32_e32 v155, v172
	v_mov_b32_e32 v171, v173
	v_pk_add_f32 v[154:155], v[154:155], v[170:171]
	v_mov_b32_e32 v170, v167
	v_mov_b32_e32 v171, v168
	v_mov_b32_e32 v167, v169
	v_pk_add_f32 v[166:167], v[170:171], v[166:167]
	v_pk_add_f32 v[154:155], v[154:155], v[154:155] op_sel:[0,1] op_sel_hi:[1,0]
	v_pk_add_f32 v[166:167], v[166:167], v[166:167] op_sel:[0,1] op_sel_hi:[1,0]
	v_mov_b32_e32 v155, v146
	v_mov_b32_e32 v167, v147
	v_mov_b32_e32 v151, v148
	v_mov_b32_e32 v153, v149
	v_pk_add_f32 v[146:147], v[154:155], v[166:167]
	v_pk_add_f32 v[148:149], v[150:151], v[152:153]
	s_nop 0
	v_pk_add_f32 v[146:147], v[146:147], v[148:149]
	s_nop 0
	v_add_f32_e32 v139, v146, v147
	v_fmamk_f32 v139, v139, 0x3a800000, v193
	v_cmp_gt_f32_e32 vcc, s40, v139
	v_mul_f32_e32 v140, 0x4b800000, v139
	s_nop 0
	v_cndmask_b32_e32 v139, v139, v140, vcc
	v_rsq_f32_e32 v139, v139
	s_nop 0
	v_mul_f32_e32 v140, 0x45800000, v139
	v_cndmask_b32_e32 v140, v139, v140, vcc

.Lzp_exit3:
	s_cmp_eq_u32 s28, s4
	s_cbranch_scc1 .Lrs_ok3
	s_mov_b32 s4, s28
	v_cmp_gt_i32_e32 vcc, 0x100, v156
	s_cbranch_vccnz .Lrs_a3
	s_bitset1_b32 s4, 8
	s_branch .Lrs_ok3
.Lrs_a3:
	v_lshl_add_u32 v146, s28, 8, v156
	v_ashrrev_i32_e32 v147, 31, v146
	v_lshlrev_b64 v[146:147], 6, v[146:147]
	v_lshl_add_u64 v[154:155], s[94:95], 0, v[146:147]
	global_load_dwordx4 v[128:131], v[154:155], off
	global_load_dwordx4 v[132:135], v[154:155], off offset:16
	global_load_dwordx4 v[136:139], v[154:155], off offset:32
	global_load_dwordx4 v[146:149], v[154:155], off offset:48
	v_lshl_add_u32 v150, v156, 2, 0
	v_add_u32_e32 v150, 0x20000, v150
	s_waitcnt vmcnt(0)
	v_mov_b32_e32 v152, v129
	v_mov_b32_e32 v153, v130
	v_mov_b32_e32 v129, v131
	v_mov_b32_e32 v130, v133
	v_mov_b32_e32 v131, v134
	v_mov_b32_e32 v133, v135
	v_pk_add_f32 v[128:129], v[152:153], v[128:129]
	v_pk_add_f32 v[130:131], v[130:131], v[132:133]
	v_pk_add_f32 v[128:129], v[128:129], v[128:129] op_sel:[0,1] op_sel_hi:[1,0]
	v_pk_add_f32 v[130:131], v[130:131], v[130:131] op_sel:[0,1] op_sel_hi:[1,0]
	v_add_f32_e32 v134, v136, v137
	v_add_f32_e32 v136, v138, v139
	v_mov_b32_e32 v135, v148
	v_mov_b32_e32 v137, v149
	v_mov_b32_e32 v129, v146
	v_mov_b32_e32 v131, v147
	v_pk_add_f32 v[132:133], v[134:135], v[136:137]
	v_pk_add_f32 v[128:129], v[128:129], v[130:131]
	s_nop 0
	v_pk_add_f32 v[128:129], v[128:129], v[132:133]
	s_nop 0
	v_add_f32_e32 v151, v128, v129
	v_fmamk_f32 v151, v151, 0x3a800000, v193
	v_mul_f32_e32 v152, 0x4b800000, v151
	v_cmp_gt_f32_e32 vcc, s40, v151
	s_nop 1
	v_cndmask_b32_e32 v151, v151, v152, vcc
	v_rsq_f32_e32 v151, v151
	s_nop 0
	v_mul_f32_e32 v152, 0x45800000, v151
	v_cndmask_b32_e32 v151, v151, v152, vcc
	ds_write_b32 v150, v151
	s_waitcnt lgkmcnt(0)
	s_barrier
.Lrs_ok3:
	s_lshl_b32 s19, s28, 8
	s_cmp_lg_u32 s28, s28
	s_cselect_b64 s[28:29], -1, 0
	v_add_u32_e32 v138, s19, v141
	s_mov_b64 s[58:59], -1
	s_and_b64 vcc, exec, s[28:29]
	s_cbranch_vccz .LBB0_795
	v_ashrrev_i32_e32 v139, 31, v138
	v_lshlrev_b64 v[146:147], 6, v[138:139]
	v_lshl_add_u64 v[154:155], s[94:95], 0, v[146:147]
	global_load_dwordx4 v[146:149], v[154:155], off offset:48
	global_load_dwordx4 v[150:153], v[154:155], off offset:32
	global_load_dwordx4 v[166:169], v[154:155], off offset:16
	global_load_dwordx4 v[170:173], v[154:155], off
	s_mov_b64 s[58:59], 0
	s_waitcnt vmcnt(0)
	v_add_f32_e32 v150, v150, v151
	v_add_f32_e32 v152, v152, v153
	v_mov_b32_e32 v154, v171
	v_mov_b32_e32 v155, v172
	v_mov_b32_e32 v171, v173
	v_pk_add_f32 v[154:155], v[154:155], v[170:171]
	v_mov_b32_e32 v170, v167
	v_mov_b32_e32 v171, v168
	v_mov_b32_e32 v167, v169
	v_pk_add_f32 v[166:167], v[170:171], v[166:167]
	v_pk_add_f32 v[154:155], v[154:155], v[154:155] op_sel:[0,1] op_sel_hi:[1,0]
	v_pk_add_f32 v[166:167], v[166:167], v[166:167] op_sel:[0,1] op_sel_hi:[1,0]
	v_mov_b32_e32 v155, v146
	v_mov_b32_e32 v167, v147
	v_mov_b32_e32 v151, v148
	v_mov_b32_e32 v153, v149
	v_pk_add_f32 v[146:147], v[154:155], v[166:167]
	v_pk_add_f32 v[148:149], v[150:151], v[152:153]
	s_nop 0
	v_pk_add_f32 v[146:147], v[146:147], v[148:149]
	s_nop 0
	v_add_f32_e32 v139, v146, v147
	v_fmamk_f32 v139, v139, 0x3a800000, v193
	v_cmp_gt_f32_e32 vcc, s40, v139
	v_mul_f32_e32 v140, 0x4b800000, v139
	s_nop 0
	v_cndmask_b32_e32 v139, v139, v140, vcc
	v_rsq_f32_e32 v139, v139
	s_nop 0
	v_mul_f32_e32 v140, 0x45800000, v139
	v_cndmask_b32_e32 v140, v139, v140, vcc
